# global seams: all-to-all top level (each XCD leader posts its generation, polls the 8 slots) instead of counter + generation word
# baseline (speedup 1.0000x reference)
.LBB0_208:
	s_andn2_saveexec_b64 s[0:1], s[10:11]
	s_cbranch_execz .LBB0_228
	s_mov_b64 s[10:11], exec
	buffer_wbl2 sc1
	s_waitcnt lgkmcnt(0)
	s_waitcnt vmcnt(0)
	buffer_inv sc1
	v_readlane_b32 s0, v248, 20
	s_cmp_eq_u32 s0, 1
	s_cbranch_scc0 .Ltop_1
	v_add_u32_e32 v1, 1, v1
	s_and_b32 s0, s2, 7
	s_lshl_b32 s0, s0, 2
	v_mov_b32_e32 v2, s0
	s_add_u32 s12, s54, 0x10080
	s_addc_u32 s13, s55, 0
	global_atomic_umax v2, v1, s[12:13]
	v_mov_b32_e32 v3, 0
	s_mov_b32 s0, 0
.Lpoll_1:
	global_load_dwordx4 v[4:7], v3, s[12:13] sc1
	global_load_dwordx4 v[8:11], v3, s[12:13] offset:16 sc1
	s_add_i32 s0, s0, 1
	s_waitcnt vmcnt(0)
	v_min3_u32 v4, v4, v5, v6
	v_min3_u32 v7, v7, v8, v9
	v_min3_u32 v4, v4, v10, v11
	v_min_u32_e32 v4, v4, v7
	v_cmp_ge_u32_e32 vcc, v4, v1
	s_cbranch_vccnz .Lland_1
	s_sleep 1
	s_cmp_lt_u32 s0, 0x8000
	s_cbranch_scc1 .Lpoll_1
	s_branch .Lland_1
.Ltop_1:
	v_mbcnt_lo_u32_b32 v1, s10, 0
	v_mbcnt_hi_u32_b32 v1, s11, v1
	v_cmp_eq_u32_e32 vcc, 0, v1
	s_and_saveexec_b64 s[12:13], vcc
	s_cbranch_execz .LBB0_211
	s_bcnt1_i32_b64 s0, s[10:11]
	v_mov_b32_e32 v2, 0x7000
	v_mov_b32_e32 v3, s0
	global_atomic_add v2, v2, v3, s[54:55] offset:1024 sc0

.Lland_2:
	s_mov_b64 s[10:11], exec
	v_mbcnt_lo_u32_b32 v0, s10, 0
	v_mbcnt_hi_u32_b32 v0, s11, v0
	v_cmp_eq_u32_e32 vcc, 0, v0
	s_waitcnt vmcnt(0)
	s_and_saveexec_b64 s[12:13], vcc
	s_cbranch_execz .LBB0_289
	s_bcnt1_i32_b64 s0, s[10:11]
	v_mov_b32_e32 v0, 0x2000
	v_mov_b32_e32 v1, s0
	global_atomic_add v0, v1, s[6:7] offset:1024

.LBB0_749:
	s_andn2_saveexec_b64 s[0:1], s[12:13]
	s_cbranch_execz .LBB0_769
	s_mov_b64 s[12:13], exec
	buffer_wbl2 sc1
	s_waitcnt lgkmcnt(0)
	s_waitcnt vmcnt(0)
	buffer_inv sc1
	v_readlane_b32 s0, v248, 20
	s_cmp_eq_u32 s0, 1
	s_cbranch_scc0 .Ltop_7
	v_add_u32_e32 v1, 1, v1
	s_and_b32 s0, s2, 7
	s_lshl_b32 s0, s0, 2
	v_mov_b32_e32 v2, s0
	s_add_u32 s14, s54, 0x10080
	s_addc_u32 s15, s55, 0
	global_atomic_umax v2, v1, s[14:15]
	v_mov_b32_e32 v3, 0
	s_mov_b32 s0, 0
.Lpoll_7:
	global_load_dwordx4 v[4:7], v3, s[14:15] sc1
	global_load_dwordx4 v[8:11], v3, s[14:15] offset:16 sc1
	s_add_i32 s0, s0, 1
	s_waitcnt vmcnt(0)
	v_min3_u32 v4, v4, v5, v6
	v_min3_u32 v7, v7, v8, v9
	v_min3_u32 v4, v4, v10, v11
	v_min_u32_e32 v4, v4, v7
	v_cmp_ge_u32_e32 vcc, v4, v1
	s_cbranch_vccnz .Lland_7
	s_sleep 1
	s_cmp_lt_u32 s0, 0x8000
	s_cbranch_scc1 .Lpoll_7
	s_branch .Lland_7
.Ltop_7:
	v_mbcnt_lo_u32_b32 v1, s12, 0
	v_mbcnt_hi_u32_b32 v1, s13, v1
	v_cmp_eq_u32_e32 vcc, 0, v1
	s_and_saveexec_b64 s[14:15], vcc
	s_cbranch_execz .LBB0_752
	s_bcnt1_i32_b64 s0, s[12:13]
	v_mov_b32_e32 v2, 0x7000
	v_mov_b32_e32 v3, s0
	global_atomic_add v2, v2, v3, s[54:55] offset:1024 sc0

.Lland_7:
	s_mov_b64 s[12:13], exec
	v_mbcnt_lo_u32_b32 v0, s12, 0
	v_mbcnt_hi_u32_b32 v0, s13, v0
	v_cmp_eq_u32_e32 vcc, 0, v0
	s_waitcnt vmcnt(0)
	s_and_saveexec_b64 s[14:15], vcc
	s_cbranch_execz .LBB0_768
	s_bcnt1_i32_b64 s0, s[12:13]
	v_mov_b32_e32 v0, 0x2000
	v_mov_b32_e32 v1, s0
	global_atomic_add v0, v1, s[10:11] offset:1024

.LBB0_1054:
	s_andn2_saveexec_b64 s[8:9], s[8:9]
	s_cbranch_execz .LBB0_1074
	s_mov_b64 s[8:9], exec
	buffer_wbl2 sc1
	s_waitcnt lgkmcnt(0)
	s_waitcnt vmcnt(0)
	buffer_inv sc1
	v_readlane_b32 s3, v248, 20
	s_cmp_eq_u32 s3, 1
	s_cbranch_scc0 .Ltop_10
	v_add_u32_e32 v1, 1, v1
	s_and_b32 s3, s2, 7
	s_lshl_b32 s3, s3, 2
	v_mov_b32_e32 v2, s3
	s_add_u32 s10, s54, 0x10080
	s_addc_u32 s11, s55, 0
	global_atomic_umax v2, v1, s[10:11]
	v_mov_b32_e32 v3, 0
	s_mov_b32 s3, 0
.Lpoll_10:
	global_load_dwordx4 v[4:7], v3, s[10:11] sc1
	global_load_dwordx4 v[8:11], v3, s[10:11] offset:16 sc1
	s_add_i32 s3, s3, 1
	s_waitcnt vmcnt(0)
	v_min3_u32 v4, v4, v5, v6
	v_min3_u32 v7, v7, v8, v9
	v_min3_u32 v4, v4, v10, v11
	v_min_u32_e32 v4, v4, v7
	v_cmp_ge_u32_e32 vcc, v4, v1
	s_cbranch_vccnz .Lland_10
	s_sleep 1
	s_cmp_lt_u32 s3, 0x8000
	s_cbranch_scc1 .Lpoll_10
	s_branch .Lland_10
.Ltop_10:
	v_mbcnt_lo_u32_b32 v1, s8, 0
	v_mbcnt_hi_u32_b32 v1, s9, v1
	v_cmp_eq_u32_e32 vcc, 0, v1
	s_and_saveexec_b64 s[10:11], vcc
	s_cbranch_execz .LBB0_1057
	s_bcnt1_i32_b64 s3, s[8:9]
	v_mov_b32_e32 v2, 0x7000
	v_mov_b32_e32 v3, s3
	global_atomic_add v2, v2, v3, s[54:55] offset:1024 sc0

.Lland_10:
	s_mov_b64 s[8:9], exec
	v_mbcnt_lo_u32_b32 v0, s8, 0
	v_mbcnt_hi_u32_b32 v0, s9, v0
	v_cmp_eq_u32_e32 vcc, 0, v0
	s_waitcnt vmcnt(0)
	s_and_saveexec_b64 s[10:11], vcc
	s_cbranch_execz .LBB0_1073
	s_bcnt1_i32_b64 s3, s[8:9]
	v_mov_b32_e32 v0, 0x2000
	v_mov_b32_e32 v1, s3
	global_atomic_add v0, v1, s[0:1] offset:1024
